# attention near-diagonal blocks: branch-free bias+mask via extended LDS bias table instead of 32 serialized exec-masked LDS lookups
# speedup vs baseline: 1.0236x; 1.0236x over previous
.LBB0_48:
	v_readlane_b32 s0, v252, 57
	s_bfe_u32 s4, s0, 0x70001
	s_bfe_u32 s0, s0, 0x20001
	v_lshl_add_u32 v2, s0, 9, v172
	v_readlane_b32 s2, v252, 62
	v_ashrrev_i32_e32 v3, 31, v2
	v_readlane_b32 s3, v252, 63
	s_waitcnt vmcnt(2)
	v_and_b32_e32 v47, 0xffff0000, v103
	v_writelane_b32 v253, s0, 0
	v_lshl_add_u64 v[2:3], v[2:3], 2, s[2:3]
	global_load_dword v1, v[2:3], off
	v_readlane_b32 s0, v252, 58
	v_readlane_b32 s1, v252, 59
	v_and_b32_e32 v2, 64, v209
	s_load_dwordx2 s[0:1], s[0:1], 0xf0
	v_add_u32_e32 v195, 64, v2
	v_lshlrev_b32_e32 v46, 16, v103
	v_mul_f32_e32 v50, v47, v47
	v_pk_fma_f32 v[58:59], v[46:47], v[46:47], v[50:51] op_sel_hi:[1,1,0]
	v_and_b32_e32 v51, 0xffff0000, v102
	v_lshlrev_b32_e32 v50, 16, v102
	v_mul_f32_e32 v54, v51, v51
	v_pk_fma_f32 v[60:61], v[50:51], v[50:51], v[54:55] op_sel_hi:[1,1,0]
	v_and_b32_e32 v55, 0xffff0000, v101
	v_and_b32_e32 v57, 0xffff0000, v100
	v_lshlrev_b32_e32 v54, 16, v101
	v_lshlrev_b32_e32 v56, 16, v100
	v_mov_b32_e32 v64, v55
	v_mov_b32_e32 v65, v57
	v_mov_b32_e32 v62, v54
	v_mov_b32_e32 v63, v56
	v_pk_mul_f32 v[64:65], v[64:65], v[64:65]
	v_and_b32_e32 v77, 0xffff0000, v106
	v_pk_fma_f32 v[66:67], v[62:63], v[62:63], v[64:65]
	v_and_b32_e32 v63, 0xffff0000, v99
	v_and_b32_e32 v65, 0xffff0000, v98
	v_lshlrev_b32_e32 v62, 16, v99
	v_lshlrev_b32_e32 v64, 16, v98
	v_mov_b32_e32 v70, v65
	v_mov_b32_e32 v71, v63
	v_mov_b32_e32 v68, v64
	v_mov_b32_e32 v69, v62
	v_pk_mul_f32 v[70:71], v[70:71], v[70:71]
	v_lshlrev_b32_e32 v76, 16, v106
	v_pk_fma_f32 v[68:69], v[68:69], v[68:69], v[70:71]
	v_and_b32_e32 v71, 0xffff0000, v108
	v_pk_add_f32 v[68:69], v[68:69], v[68:69] op_sel:[0,1] op_sel_hi:[1,0]
	v_lshlrev_b32_e32 v70, 16, v108
	v_pk_add_f32 v[68:69], v[66:67], v[68:69] op_sel:[1,0] op_sel_hi:[0,1]
	v_pk_add_f32 v[66:67], v[66:67], v[68:69]
	v_and_b32_e32 v69, 0xffff0000, v109
	v_lshlrev_b32_e32 v68, 16, v109
	v_mov_b32_e32 v74, v69
	v_mov_b32_e32 v75, v71
	v_mov_b32_e32 v72, v68
	v_mov_b32_e32 v73, v70
	v_pk_mul_f32 v[74:75], v[74:75], v[74:75]
	v_mov_b32_e32 v80, v77
	v_pk_fma_f32 v[72:73], v[72:73], v[72:73], v[74:75]
	v_and_b32_e32 v75, 0xffff0000, v107
	v_lshlrev_b32_e32 v74, 16, v107
	v_mov_b32_e32 v81, v75
	v_mov_b32_e32 v78, v76
	v_mov_b32_e32 v79, v74
	v_pk_mul_f32 v[80:81], v[80:81], v[80:81]
	s_waitcnt vmcnt(2)
	v_and_b32_e32 v37, 0xffff0000, v112
	v_pk_fma_f32 v[78:79], v[78:79], v[78:79], v[80:81]
	v_and_b32_e32 v43, 0xffff0000, v105
	v_pk_add_f32 v[78:79], v[78:79], v[78:79] op_sel:[0,1] op_sel_hi:[1,0]
	v_lshlrev_b32_e32 v36, 16, v112
	v_lshlrev_b32_e32 v38, 16, v111
	v_and_b32_e32 v39, 0xffff0000, v111
	v_and_b32_e32 v41, 0xffff0000, v110
	v_lshlrev_b32_e32 v42, 16, v105
	v_and_b32_e32 v45, 0xffff0000, v104
	v_pk_add_f32 v[78:79], v[72:73], v[78:79] op_sel:[1,0] op_sel_hi:[0,1]
	v_mov_b32_e32 v80, v43
	v_mov_b32_e32 v81, v37
	v_pk_mul_f32 v[52:53], v[38:39], v[38:39]
	v_lshlrev_b32_e32 v40, 16, v110
	v_lshlrev_b32_e32 v44, 16, v104
	v_pk_add_f32 v[72:73], v[72:73], v[78:79]
	v_mov_b32_e32 v78, v42
	v_mov_b32_e32 v79, v36
	v_pk_mul_f32 v[80:81], v[80:81], v[80:81]
	v_mov_b32_e32 v82, v45
	v_mov_b32_e32 v83, v41
	v_lshlrev_b32_e32 v34, 16, v113
	v_and_b32_e32 v35, 0xffff0000, v113
	v_pk_fma_f32 v[78:79], v[78:79], v[78:79], v[80:81]
	s_waitcnt vmcnt(0)
	v_mul_f32_e32 v1, 0x3fb8aa3b, v1
	ds_write_b32 v169, v1
	v_lshrrev_b32_e32 v2, 7, v172
	v_lshlrev_b32_e32 v3, 2, v172
	v_lshl_add_u32 v3, v2, 9, v3
	v_bfe_u32 v4, v172, 6, 1
	v_readlane_b32 s100, v1, 63
	v_add_u32_e32 v5, 0x22200, v3
	ds_write_b32 v5, v1
	v_lshl_add_u32 v3, v4, 9, v3
	v_cmp_ne_u32_e32 vcc, 0, v4
	v_mov_b32_e32 v5, s100
	v_add_u32_e32 v3, 0x22100, v3
	v_cndmask_b32_e32 v5, v210, v5, vcc
	ds_write_b32 v3, v5
	v_xor_b32_e32 v1, 32, v209
	v_cmp_lt_i32_e32 vcc, v1, v195
	v_mov_b32_e32 v80, v44
	v_mov_b32_e32 v81, v40
	v_cndmask_b32_e32 v1, v209, v1, vcc
	v_lshlrev_b32_e32 v163, 2, v1
	v_lshlrev_b32_e32 v1, 2, v174
	s_waitcnt lgkmcnt(0)
	global_load_dwordx4 v[26:29], v1, s[0:1] offset:16
	global_load_dwordx4 v[30:33], v1, s[0:1]
	global_load_dwordx4 v[18:21], v1, s[0:1] offset:80
	global_load_dwordx4 v[22:25], v1, s[0:1] offset:64
	global_load_dwordx4 v[10:13], v1, s[0:1] offset:144
	global_load_dwordx4 v[14:17], v1, s[0:1] offset:128
	global_load_dwordx4 v[2:5], v1, s[0:1] offset:208
	global_load_dwordx4 v[6:9], v1, s[0:1] offset:192
	v_pk_mul_f32 v[82:83], v[82:83], v[82:83]
	v_mov_b32_e32 v61, v52
	v_mov_b32_e32 v59, v53
	v_pk_mul_f32 v[48:49], v[34:35], v[34:35]
	v_pk_fma_f32 v[80:81], v[80:81], v[80:81], v[82:83]
	v_pk_add_f32 v[52:53], v[60:61], v[58:59]
	v_mov_b32_e32 v73, v48
	v_pk_add_f32 v[52:53], v[80:81], v[52:53]
	v_mov_b32_e32 v67, v49
	v_pk_add_f32 v[52:53], v[78:79], v[52:53]
	v_pk_add_f32 v[48:49], v[72:73], v[66:67]
	s_mov_b32 s0, 0x800000
	v_pk_add_f32 v[48:49], v[48:49], v[52:53]
	s_lshl_b32 s5, s50, 6
	v_add_f32_e32 v1, v48, v49
	ds_bpermute_b32 v48, v163, v1
	v_lshlrev_b32_e32 v96, 1, v174
	v_mov_b32_e32 v187, v97
	s_waitcnt lgkmcnt(0)
	s_barrier
	v_add_f32_e32 v1, v1, v48
	v_fmamk_f32 v1, v1, 0x3c800000, v207
	v_cmp_gt_f32_e32 vcc, s0, v1
	v_mul_f32_e32 v48, 0x4b800000, v1
	s_lshl_b32 s0, s4, 14
	v_cndmask_b32_e32 v1, v1, v48, vcc
	v_rsq_f32_e32 v1, v1
	s_add_u32 s0, s2, s0
	s_addc_u32 s1, s3, 0
	v_mul_f32_e32 v48, 0x45800000, v1
	v_cndmask_b32_e32 v1, v1, v48, vcc
	v_mul_f32_e32 v48, 0x3e38aa3b, v1
	v_pk_mul_f32 v[52:53], v[48:49], v[76:77] op_sel_hi:[0,1]
	v_mul_f32_e32 v0, 0xbfb8aa3b, v164
	v_writelane_b32 v253, s4, 1
	s_waitcnt vmcnt(6)
	v_pk_mul_f32 v[30:31], v[30:31], v[52:53]
	s_nop 0
	v_cvt_pk_bf16_f32 v114, v30, v31
	v_pk_mul_f32 v[30:31], v[48:49], v[74:75] op_sel_hi:[0,1]
	v_pk_mul_f32 v[30:31], v[32:33], v[30:31]
	s_nop 0
	v_cvt_pk_bf16_f32 v115, v30, v31
	v_pk_mul_f32 v[30:31], v[48:49], v[70:71] op_sel_hi:[0,1]
	v_pk_mul_f32 v[26:27], v[26:27], v[30:31]
	s_nop 0
	v_cvt_pk_bf16_f32 v116, v26, v27
	v_pk_mul_f32 v[26:27], v[48:49], v[68:69] op_sel_hi:[0,1]
	v_pk_mul_f32 v[26:27], v[28:29], v[26:27]
	s_nop 0
	v_cvt_pk_bf16_f32 v117, v26, v27
	v_pk_mul_f32 v[26:27], v[48:49], v[64:65] op_sel_hi:[0,1]
	s_waitcnt vmcnt(4)
	v_pk_mul_f32 v[22:23], v[22:23], v[26:27]
	s_nop 0
	v_cvt_pk_bf16_f32 v118, v22, v23
	v_pk_mul_f32 v[22:23], v[48:49], v[62:63] op_sel_hi:[0,1]
	v_pk_mul_f32 v[22:23], v[24:25], v[22:23]
	s_nop 0
	v_cvt_pk_bf16_f32 v119, v22, v23
	v_pk_mul_f32 v[22:23], v[48:49], v[56:57] op_sel_hi:[0,1]
	v_pk_mul_f32 v[18:19], v[18:19], v[22:23]
	s_nop 0
	v_cvt_pk_bf16_f32 v120, v18, v19
	v_pk_mul_f32 v[18:19], v[48:49], v[54:55] op_sel_hi:[0,1]
	v_pk_mul_f32 v[18:19], v[20:21], v[18:19]
	s_nop 0
	v_cvt_pk_bf16_f32 v121, v18, v19
	v_pk_mul_f32 v[18:19], v[48:49], v[50:51] op_sel_hi:[0,1]
	s_waitcnt vmcnt(2)
	v_pk_mul_f32 v[14:15], v[14:15], v[18:19]
	s_nop 0
	v_cvt_pk_bf16_f32 v122, v14, v15
	v_pk_mul_f32 v[14:15], v[48:49], v[46:47] op_sel_hi:[0,1]
	v_pk_mul_f32 v[14:15], v[16:17], v[14:15]
	s_nop 0
	v_cvt_pk_bf16_f32 v123, v14, v15
	v_pk_mul_f32 v[14:15], v[48:49], v[44:45] op_sel_hi:[0,1]
	v_pk_mul_f32 v[10:11], v[10:11], v[14:15]
	s_nop 0
	v_cvt_pk_bf16_f32 v124, v10, v11
	v_pk_mul_f32 v[10:11], v[48:49], v[42:43] op_sel_hi:[0,1]
	v_pk_mul_f32 v[10:11], v[12:13], v[10:11]
	s_nop 0
	v_cvt_pk_bf16_f32 v125, v10, v11
	v_pk_mul_f32 v[10:11], v[48:49], v[40:41] op_sel_hi:[0,1]
	s_waitcnt vmcnt(0)
	v_pk_mul_f32 v[6:7], v[6:7], v[10:11]
	s_nop 0
	v_cvt_pk_bf16_f32 v126, v6, v7
	v_pk_mul_f32 v[6:7], v[48:49], v[38:39] op_sel_hi:[0,1]
	v_pk_mul_f32 v[6:7], v[8:9], v[6:7]
	s_nop 0
	v_cvt_pk_bf16_f32 v127, v6, v7
	v_pk_mul_f32 v[6:7], v[48:49], v[36:37] op_sel_hi:[0,1]
	v_pk_mul_f32 v[2:3], v[2:3], v[6:7]
	s_nop 0
	v_cvt_pk_bf16_f32 v128, v2, v3
	v_pk_mul_f32 v[2:3], v[48:49], v[34:35] op_sel_hi:[0,1]
	v_pk_mul_f32 v[2:3], v[4:5], v[2:3]
	s_nop 0
	v_cvt_pk_bf16_f32 v129, v2, v3
	v_lshl_add_u64 v[2:3], s[0:1], 0, v[96:97]
	v_lshl_add_u64 v[80:81], v[2:3], 0, v[186:187]
	s_mov_b64 s[0:1], 0x5000000
	v_lshl_add_u64 v[2:3], v[80:81], 0, s[0:1]
	s_mov_b32 s0, 0x5001000
	v_add_co_u32_e32 v4, vcc, s0, v80
	s_nop 1
	v_addc_co_u32_e32 v5, vcc, 0, v81, vcc
	global_load_dwordx4 v[16:19], v[4:5], off offset:-4096
	global_load_dwordx4 v[24:27], v[2:3], off offset:32
	global_load_dwordx4 v[20:23], v[2:3], off offset:64
	global_load_dwordx4 v[28:31], v[2:3], off offset:96
	global_load_dwordx4 v[64:67], v[4:5], off
	global_load_dwordx4 v[68:71], v[4:5], off offset:32
	global_load_dwordx4 v[72:75], v[4:5], off offset:64
	global_load_dwordx4 v[76:79], v[4:5], off offset:96
	v_mov_b32_e32 v1, v0
	v_mov_b32_e32 v2, v0
	v_mov_b32_e32 v3, v0
	v_mov_b32_e32 v4, v0
	v_mov_b32_e32 v5, v0
	v_mov_b32_e32 v6, v0
	v_mov_b32_e32 v7, v0
	v_mov_b32_e32 v8, v0
	v_mov_b32_e32 v9, v0
	v_mov_b32_e32 v10, v0
	v_mov_b32_e32 v11, v0
	v_mov_b32_e32 v12, v0
	v_mov_b32_e32 v13, v0
	v_mov_b32_e32 v14, v0
	v_mov_b32_e32 v15, v0
	s_mov_b32 s0, 0x5002000
	s_waitcnt vmcnt(3)
	v_mfma_f32_32x32x16_bf16 v[32:47], v[64:67], v[114:117], v[0:15]
	s_waitcnt vmcnt(2)
	v_mfma_f32_32x32x16_bf16 v[32:47], v[68:71], v[118:121], v[32:47]
	s_waitcnt vmcnt(1)
	v_mfma_f32_32x32x16_bf16 v[32:47], v[72:75], v[122:125], v[32:47]
	v_mfma_f32_32x32x16_bf16 v[48:63], v[16:19], v[114:117], v[0:15]
	v_add_co_u32_e32 v16, vcc, s0, v80
	s_mov_b32 s0, 0x5003000
	s_nop 0
	v_addc_co_u32_e32 v17, vcc, 0, v81, vcc
	v_add_co_u32_e32 v18, vcc, s0, v80
	s_waitcnt vmcnt(0)
	v_mfma_f32_32x32x16_bf16 v[32:47], v[76:79], v[126:129], v[32:47]
	v_addc_co_u32_e32 v19, vcc, 0, v81, vcc
	global_load_dwordx4 v[64:67], v[18:19], off offset:-4096
	global_load_dwordx4 v[68:71], v[16:17], off offset:32
	global_load_dwordx4 v[72:75], v[16:17], off offset:64
	global_load_dwordx4 v[76:79], v[16:17], off offset:96
	global_load_dwordx4 v[80:83], v[18:19], off
	global_load_dwordx4 v[84:87], v[18:19], off offset:32
	global_load_dwordx4 v[88:91], v[18:19], off offset:64
	global_load_dwordx4 v[92:95], v[18:19], off offset:96
	v_mfma_f32_32x32x16_bf16 v[48:63], v[24:27], v[118:121], v[48:63]
	v_mfma_f32_32x32x16_bf16 v[48:63], v[20:23], v[122:125], v[48:63]
	v_mfma_f32_32x32x16_bf16 v[48:63], v[28:31], v[126:129], v[48:63]
	s_waitcnt vmcnt(7)
	v_mfma_f32_32x32x16_bf16 v[16:31], v[64:67], v[114:117], v[0:15]
	v_or_b32_e32 v164, s5, v167
	v_sub_u32_e32 v66, v164, v175
	v_subrev_u32_e32 v67, 31, v66
	v_writelane_b32 v253, s5, 2
	v_cmp_lt_i32_e32 vcc, -1, v67
	v_mov_b32_e32 v64, 0
	v_mov_b32_e32 v65, 0
	s_waitcnt vmcnt(3)
	v_mfma_f32_32x32x16_bf16 v[0:15], v[80:83], v[114:117], v[0:15]
	v_mfma_f32_32x32x16_bf16 v[16:31], v[68:71], v[118:121], v[16:31]
	s_waitcnt vmcnt(2)
	v_mfma_f32_32x32x16_bf16 v[0:15], v[84:87], v[118:121], v[0:15]
	v_mfma_f32_32x32x16_bf16 v[16:31], v[72:75], v[122:125], v[16:31]
	s_waitcnt vmcnt(1)
	v_mfma_f32_32x32x16_bf16 v[0:15], v[88:91], v[122:125], v[0:15]
	v_mfma_f32_32x32x16_bf16 v[16:31], v[76:79], v[126:129], v[16:31]
	s_waitcnt vmcnt(0)
	v_mfma_f32_32x32x16_bf16 v[0:15], v[92:95], v[126:129], v[0:15]
	s_and_saveexec_b64 s[0:1], vcc
	s_cbranch_execz .LBB0_50
	v_min_u32_e32 v65, 0x7f, v67
	v_lshl_add_u32 v65, v65, 2, s33
	ds_read_b32 v65, v65
	s_waitcnt lgkmcnt(0)
	v_add_f32_e32 v48, v48, v65
	v_exp_f32_e32 v65, v48

.LBB0_402:
	s_add_i32 s9, s8, -2
	v_add_u32_e32 v64, s0, v227
	v_add_u32_e32 v157, s1, v174
	s_cmp_lt_i32 s9, 0
	v_add_u32_e32 v160, v64, v229
	s_cbranch_scc1 .LBB0_472
	ds_read_b128 v[0:3], v160
	ds_read_b128 v[4:7], v160 offset:32
	ds_read_b128 v[8:11], v160 offset:64
	ds_read_b128 v[12:15], v160 offset:96
	ds_read_b128 v[16:19], v160 offset:4608
	ds_read_b128 v[20:23], v160 offset:4640
	ds_read_b128 v[24:27], v160 offset:4672
	ds_read_b128 v[28:31], v160 offset:4704
	v_lshrrev_b32_e32 v64, s9, v147
	v_and_b32_e32 v64, 1, v64
	v_cmp_eq_u32_e32 vcc, 1, v64
	s_cmp_lt_i32 s9, s51
	s_cselect_b64 s[88:89], -1, 0
	v_cndmask_b32_e32 v64, v210, v149, vcc
	v_cndmask_b32_e32 v65, v210, v151, vcc
	v_add_f32_e32 v64, v151, v64
	v_cndmask_b32_e64 v64, v65, v64, s[88:89]
	s_cmp_ge_i32 s9, s51
	s_setprio 1
	v_mov_b32_e32 v65, v64
	v_mov_b32_e32 v66, v64
	v_mov_b32_e32 v67, v64
	v_mov_b32_e32 v68, v64
	v_mov_b32_e32 v69, v64
	v_mov_b32_e32 v70, v64
	v_mov_b32_e32 v71, v64
	v_mov_b32_e32 v72, v64
	v_mov_b32_e32 v73, v64
	v_mov_b32_e32 v74, v64
	v_mov_b32_e32 v75, v64
	v_mov_b32_e32 v76, v64
	v_mov_b32_e32 v77, v64
	v_mov_b32_e32 v78, v64
	v_mov_b32_e32 v79, v64
	s_waitcnt lgkmcnt(7)
	s_nop 0
	v_mfma_f32_32x32x16_bf16 v[80:95], v[0:3], v[114:117], v[64:79]
	s_waitcnt lgkmcnt(3)
	v_mfma_f32_32x32x16_bf16 v[64:79], v[16:19], v[114:117], v[64:79]
	v_mfma_f32_32x32x16_bf16 v[80:95], v[4:7], v[118:121], v[80:95]
	s_waitcnt lgkmcnt(2)
	v_mfma_f32_32x32x16_bf16 v[64:79], v[20:23], v[118:121], v[64:79]
	v_mfma_f32_32x32x16_bf16 v[80:95], v[8:11], v[122:125], v[80:95]
	s_waitcnt lgkmcnt(1)
	v_mfma_f32_32x32x16_bf16 v[64:79], v[24:27], v[122:125], v[64:79]
	v_mfma_f32_32x32x16_bf16 v[80:95], v[12:15], v[126:129], v[80:95]
	s_waitcnt lgkmcnt(0)
	v_mfma_f32_32x32x16_bf16 v[64:79], v[28:31], v[126:129], v[64:79]
	s_setprio 0
	s_mov_b64 s[0:1], -1
	s_cbranch_scc0 .LBB0_469
	s_lshl_b32 s0, s33, 1
	s_add_i32 s0, s0, 0xfffff180
	v_lshl_add_u32 v31, v158, 2, s0
	ds_read_b32 v0, v31 offset:236
	ds_read_b32 v1, v31 offset:232
	ds_read_b32 v2, v31 offset:228
	ds_read_b32 v3, v31 offset:224
	ds_read_b32 v4, v31 offset:204
	ds_read_b32 v5, v31 offset:200
	ds_read_b32 v6, v31 offset:196
	ds_read_b32 v7, v31 offset:192
	ds_read_b32 v8, v31 offset:172
	ds_read_b32 v9, v31 offset:168
	ds_read_b32 v10, v31 offset:164
	ds_read_b32 v11, v31 offset:160
	ds_read_b32 v12, v31 offset:140
	ds_read_b32 v13, v31 offset:136
	ds_read_b32 v14, v31 offset:132
	s_waitcnt lgkmcnt(7)
	v_add_f32_e32 v0, v80, v0
	v_add_f32_e32 v1, v81, v1
	v_add_f32_e32 v2, v82, v2
	v_add_f32_e32 v3, v83, v3
	v_add_f32_e32 v4, v84, v4
	v_add_f32_e32 v5, v85, v5
	v_add_f32_e32 v6, v86, v6
	v_add_f32_e32 v7, v87, v7
	ds_read_b32 v15, v31 offset:128
	ds_read_b32 v16, v31 offset:108
	ds_read_b32 v17, v31 offset:104
	ds_read_b32 v18, v31 offset:100
	ds_read_b32 v19, v31 offset:96
	ds_read_b32 v20, v31 offset:76
	ds_read_b32 v21, v31 offset:72
	ds_read_b32 v22, v31 offset:68
	v_exp_f32_e32 v0, v0
	v_exp_f32_e32 v1, v1
	v_exp_f32_e32 v2, v2
	v_exp_f32_e32 v3, v3
	v_exp_f32_e32 v4, v4
	v_exp_f32_e32 v5, v5
	v_exp_f32_e32 v6, v6
	v_exp_f32_e32 v7, v7
	s_waitcnt lgkmcnt(8)
	v_add_f32_e32 v8, v88, v8
	v_add_f32_e32 v9, v89, v9
	v_add_f32_e32 v10, v90, v10
	v_add_f32_e32 v11, v91, v11
	v_add_f32_e32 v12, v92, v12
	v_add_f32_e32 v13, v93, v13
	v_add_f32_e32 v14, v94, v14
	ds_read_b32 v23, v31 offset:64
	ds_read_b32 v24, v31 offset:44
	ds_read_b32 v25, v31 offset:40
	ds_read_b32 v26, v31 offset:36
	ds_read_b32 v27, v31 offset:32
	ds_read_b32 v28, v31 offset:12
	ds_read_b32 v29, v31 offset:8
	v_exp_f32_e32 v8, v8
	v_add_f32_e32 v161, v159, v0
	v_exp_f32_e32 v9, v9
	v_add_f32_e32 v161, v161, v1
	v_exp_f32_e32 v10, v10
	v_add_f32_e32 v161, v161, v2
	v_exp_f32_e32 v11, v11
	v_add_f32_e32 v161, v161, v3
	v_exp_f32_e32 v12, v12
	v_add_f32_e32 v161, v161, v4
	v_exp_f32_e32 v13, v13
	v_add_f32_e32 v161, v161, v5
	v_exp_f32_e32 v14, v14
	v_add_f32_e32 v161, v161, v6
	v_add_f32_e32 v161, v161, v7
	s_waitcnt lgkmcnt(7)
	v_add_f32_e32 v15, v95, v15
	v_add_f32_e32 v16, v64, v16
	v_add_f32_e32 v17, v65, v17
	v_add_f32_e32 v18, v66, v18
	v_add_f32_e32 v19, v67, v19
	v_add_f32_e32 v20, v68, v20
	v_add_f32_e32 v21, v69, v21
	v_add_f32_e32 v22, v70, v22
	ds_read_b32 v30, v31 offset:4
	ds_read_b32 v31, v31 offset:0
	v_exp_f32_e32 v15, v15
	v_add_f32_e32 v161, v161, v8
	v_exp_f32_e32 v16, v16
	v_add_f32_e32 v161, v161, v9
	v_exp_f32_e32 v17, v17
	v_add_f32_e32 v161, v161, v10
	v_exp_f32_e32 v18, v18
	v_add_f32_e32 v161, v161, v11
	v_exp_f32_e32 v19, v19
	v_add_f32_e32 v161, v161, v12
	v_exp_f32_e32 v20, v20
	v_add_f32_e32 v161, v161, v13
	v_exp_f32_e32 v21, v21
	v_add_f32_e32 v161, v161, v14
	v_exp_f32_e32 v22, v22
	s_waitcnt lgkmcnt(2)
	v_add_f32_e32 v23, v71, v23
	v_add_f32_e32 v24, v72, v24
	v_add_f32_e32 v25, v73, v25
	v_add_f32_e32 v26, v74, v26
	v_add_f32_e32 v27, v75, v27
	v_add_f32_e32 v28, v76, v28
	v_add_f32_e32 v29, v77, v29
	v_exp_f32_e32 v23, v23
	v_add_f32_e32 v161, v161, v15
	v_exp_f32_e32 v24, v24
	v_add_f32_e32 v161, v161, v16
	v_exp_f32_e32 v25, v25
	v_add_f32_e32 v161, v161, v17
	v_exp_f32_e32 v26, v26
	v_add_f32_e32 v161, v161, v18
	v_exp_f32_e32 v27, v27
	v_add_f32_e32 v161, v161, v19
	v_exp_f32_e32 v28, v28
	v_add_f32_e32 v161, v161, v20
	v_exp_f32_e32 v29, v29
	v_add_f32_e32 v161, v161, v21
	v_add_f32_e32 v161, v161, v22
	s_waitcnt lgkmcnt(0)
	v_add_f32_e32 v30, v78, v30
	v_add_f32_e32 v31, v79, v31
	v_exp_f32_e32 v30, v30
	v_add_f32_e32 v161, v161, v23
	v_exp_f32_e32 v31, v31
	v_add_f32_e32 v161, v161, v24
	v_add_f32_e32 v161, v161, v25
	v_add_f32_e32 v161, v161, v26
	v_add_f32_e32 v161, v161, v27
	v_add_f32_e32 v161, v161, v28
	v_add_f32_e32 v161, v161, v29
	v_add_f32_e32 v161, v161, v30
	v_add_f32_e32 v161, v161, v31
	s_mov_b64 s[0:1], 0

.LBB0_473:
	ds_read_b128 v[32:35], v160 offset:9216
	ds_read_b128 v[36:39], v160 offset:9248
	ds_read_b128 v[40:43], v160 offset:9280
	ds_read_b128 v[44:47], v160 offset:9312
	ds_read_b128 v[48:51], v160 offset:13824
	ds_read_b128 v[52:55], v160 offset:13856
	ds_read_b128 v[56:59], v160 offset:13888
	ds_read_b128 v[60:63], v160 offset:13920
	s_add_i32 s0, s8, -1
	v_lshrrev_b32_e32 v64, s0, v147
	v_and_b32_e32 v64, 1, v64
	v_cmp_eq_u32_e64 s[88:89], 1, v64
	s_cmp_lt_i32 s0, s51
	s_cselect_b64 vcc, -1, 0
	v_cndmask_b32_e64 v64, v210, v149, s[88:89]
	v_cndmask_b32_e64 v65, v210, v151, s[88:89]
	v_add_f32_e32 v64, v151, v64
	v_cndmask_b32_e32 v64, v65, v64, vcc
	s_setprio 1
	v_mov_b32_e32 v65, v64
	v_mov_b32_e32 v66, v64
	v_mov_b32_e32 v67, v64
	v_mov_b32_e32 v68, v64
	v_mov_b32_e32 v69, v64
	v_mov_b32_e32 v70, v64
	v_mov_b32_e32 v71, v64
	v_mov_b32_e32 v72, v64
	v_mov_b32_e32 v73, v64
	v_mov_b32_e32 v74, v64
	v_mov_b32_e32 v75, v64
	v_mov_b32_e32 v76, v64
	v_mov_b32_e32 v77, v64
	v_mov_b32_e32 v78, v64
	v_mov_b32_e32 v79, v64
	s_waitcnt lgkmcnt(7)
	s_nop 0
	v_mfma_f32_32x32x16_bf16 v[80:95], v[32:35], v[114:117], v[64:79]
	s_waitcnt lgkmcnt(3)
	v_mfma_f32_32x32x16_bf16 v[64:79], v[48:51], v[114:117], v[64:79]
	v_mfma_f32_32x32x16_bf16 v[80:95], v[36:39], v[118:121], v[80:95]
	s_waitcnt lgkmcnt(2)
	v_mfma_f32_32x32x16_bf16 v[64:79], v[52:55], v[118:121], v[64:79]
	v_mfma_f32_32x32x16_bf16 v[80:95], v[40:43], v[122:125], v[80:95]
	s_waitcnt lgkmcnt(1)
	v_mfma_f32_32x32x16_bf16 v[64:79], v[56:59], v[122:125], v[64:79]
	v_mfma_f32_32x32x16_bf16 v[80:95], v[44:47], v[126:129], v[80:95]
	s_waitcnt lgkmcnt(0)
	v_mfma_f32_32x32x16_bf16 v[64:79], v[60:63], v[126:129], v[64:79]
	s_setprio 0
	s_mov_b64 s[0:1], -1
	s_and_b64 vcc, exec, vcc
	s_cbranch_vccnz .LBB0_539
	s_lshl_b32 s0, s33, 1
	s_add_i32 s0, s0, 0xfffff080
	v_lshl_add_u32 v63, v158, 2, s0
	ds_read_b32 v32, v63 offset:236
	ds_read_b32 v33, v63 offset:232
	ds_read_b32 v34, v63 offset:228
	ds_read_b32 v35, v63 offset:224
	ds_read_b32 v36, v63 offset:204
	ds_read_b32 v37, v63 offset:200
	ds_read_b32 v38, v63 offset:196
	ds_read_b32 v39, v63 offset:192
	ds_read_b32 v40, v63 offset:172
	ds_read_b32 v41, v63 offset:168
	ds_read_b32 v42, v63 offset:164
	ds_read_b32 v43, v63 offset:160
	ds_read_b32 v44, v63 offset:140
	ds_read_b32 v45, v63 offset:136
	ds_read_b32 v46, v63 offset:132
	s_waitcnt lgkmcnt(7)
	v_add_f32_e32 v32, v80, v32
	v_add_f32_e32 v33, v81, v33
	v_add_f32_e32 v34, v82, v34
	v_add_f32_e32 v35, v83, v35
	v_add_f32_e32 v36, v84, v36
	v_add_f32_e32 v37, v85, v37
	v_add_f32_e32 v38, v86, v38
	v_add_f32_e32 v39, v87, v39
	ds_read_b32 v47, v63 offset:128
	ds_read_b32 v48, v63 offset:108
	ds_read_b32 v49, v63 offset:104
	ds_read_b32 v50, v63 offset:100
	ds_read_b32 v51, v63 offset:96
	ds_read_b32 v52, v63 offset:76
	ds_read_b32 v53, v63 offset:72
	ds_read_b32 v54, v63 offset:68
	v_exp_f32_e32 v32, v32
	v_exp_f32_e32 v33, v33
	v_exp_f32_e32 v34, v34
	v_exp_f32_e32 v35, v35
	v_exp_f32_e32 v36, v36
	v_exp_f32_e32 v37, v37
	v_exp_f32_e32 v38, v38
	v_exp_f32_e32 v39, v39
	s_waitcnt lgkmcnt(8)
	v_add_f32_e32 v40, v88, v40
	v_add_f32_e32 v41, v89, v41
	v_add_f32_e32 v42, v90, v42
	v_add_f32_e32 v43, v91, v43
	v_add_f32_e32 v44, v92, v44
	v_add_f32_e32 v45, v93, v45
	v_add_f32_e32 v46, v94, v46
	ds_read_b32 v55, v63 offset:64
	ds_read_b32 v56, v63 offset:44
	ds_read_b32 v57, v63 offset:40
	ds_read_b32 v58, v63 offset:36
	ds_read_b32 v59, v63 offset:32
	ds_read_b32 v60, v63 offset:12
	ds_read_b32 v61, v63 offset:8
	v_exp_f32_e32 v40, v40
	v_add_f32_e32 v159, v161, v32
	v_exp_f32_e32 v41, v41
	v_add_f32_e32 v159, v159, v33
	v_exp_f32_e32 v42, v42
	v_add_f32_e32 v159, v159, v34
	v_exp_f32_e32 v43, v43
	v_add_f32_e32 v159, v159, v35
	v_exp_f32_e32 v44, v44
	v_add_f32_e32 v159, v159, v36
	v_exp_f32_e32 v45, v45
	v_add_f32_e32 v159, v159, v37
	v_exp_f32_e32 v46, v46
	v_add_f32_e32 v159, v159, v38
	v_add_f32_e32 v159, v159, v39
	s_waitcnt lgkmcnt(7)
	v_add_f32_e32 v47, v95, v47
	v_add_f32_e32 v48, v64, v48
	v_add_f32_e32 v49, v65, v49
	v_add_f32_e32 v50, v66, v50
	v_add_f32_e32 v51, v67, v51
	v_add_f32_e32 v52, v68, v52
	v_add_f32_e32 v53, v69, v53
	v_add_f32_e32 v54, v70, v54
	ds_read_b32 v62, v63 offset:4
	ds_read_b32 v63, v63 offset:0
	v_exp_f32_e32 v47, v47
	v_add_f32_e32 v159, v159, v40
	v_exp_f32_e32 v48, v48
	v_add_f32_e32 v159, v159, v41
	v_exp_f32_e32 v49, v49
	v_add_f32_e32 v159, v159, v42
	v_exp_f32_e32 v50, v50
	v_add_f32_e32 v159, v159, v43
	v_exp_f32_e32 v51, v51
	v_add_f32_e32 v159, v159, v44
	v_exp_f32_e32 v52, v52
	v_add_f32_e32 v159, v159, v45
	v_exp_f32_e32 v53, v53
	v_add_f32_e32 v159, v159, v46
	v_exp_f32_e32 v54, v54
	s_waitcnt lgkmcnt(2)
	v_add_f32_e32 v55, v71, v55
	v_add_f32_e32 v56, v72, v56
	v_add_f32_e32 v57, v73, v57
	v_add_f32_e32 v58, v74, v58
	v_add_f32_e32 v59, v75, v59
	v_add_f32_e32 v60, v76, v60
	v_add_f32_e32 v61, v77, v61
	v_exp_f32_e32 v55, v55
	v_add_f32_e32 v159, v159, v47
	v_exp_f32_e32 v56, v56
	v_add_f32_e32 v159, v159, v48
	v_exp_f32_e32 v57, v57
	v_add_f32_e32 v159, v159, v49
	v_exp_f32_e32 v58, v58
	v_add_f32_e32 v159, v159, v50
	v_exp_f32_e32 v59, v59
	v_add_f32_e32 v159, v159, v51
	v_exp_f32_e32 v60, v60
	v_add_f32_e32 v159, v159, v52
	v_exp_f32_e32 v61, v61
	v_add_f32_e32 v159, v159, v53
	v_add_f32_e32 v159, v159, v54
	s_waitcnt lgkmcnt(0)
	v_add_f32_e32 v62, v78, v62
	v_add_f32_e32 v63, v79, v63
	v_exp_f32_e32 v62, v62
	v_add_f32_e32 v159, v159, v55
	v_exp_f32_e32 v63, v63
	v_add_f32_e32 v159, v159, v56
	v_add_f32_e32 v159, v159, v57
	v_add_f32_e32 v159, v159, v58
	v_add_f32_e32 v159, v159, v59
	v_add_f32_e32 v159, v159, v60
	v_add_f32_e32 v159, v159, v61
	v_add_f32_e32 v159, v159, v62
	v_add_f32_e32 v159, v159, v63
	s_mov_b64 s[0:1], 0

.LBB0_550:
	s_andn2_b64 vcc, exec, s[2:3]
	s_cbranch_vccnz .LBB0_619
	s_lshl_b32 s2, s8, 6
	v_subrev_u32_e32 v0, s2, v228
	v_add_u32_e32 v155, v0, v164
	s_mov_b64 s[2:3], -1
	s_and_b64 vcc, exec, s[0:1]
	s_cbranch_vccz .LBB0_617
	s_lshl_b32 s0, s33, 1
	s_add_i32 s0, s0, 0xfffff114
	v_lshl_add_u32 v31, v155, 2, s0
	ds_read_b32 v0, v31 offset:236
	ds_read_b32 v1, v31 offset:232
	ds_read_b32 v2, v31 offset:228
	ds_read_b32 v3, v31 offset:224
	ds_read_b32 v4, v31 offset:204
	ds_read_b32 v5, v31 offset:200
	ds_read_b32 v6, v31 offset:196
	ds_read_b32 v7, v31 offset:192
	ds_read_b32 v8, v31 offset:172
	ds_read_b32 v9, v31 offset:168
	ds_read_b32 v10, v31 offset:164
	ds_read_b32 v11, v31 offset:160
	ds_read_b32 v12, v31 offset:140
	ds_read_b32 v13, v31 offset:136
	ds_read_b32 v14, v31 offset:132
	s_waitcnt lgkmcnt(7)
	v_add_f32_e32 v0, v80, v0
	v_add_f32_e32 v1, v81, v1
	v_add_f32_e32 v2, v82, v2
	v_add_f32_e32 v3, v83, v3
	v_add_f32_e32 v4, v84, v4
	v_add_f32_e32 v5, v85, v5
	v_add_f32_e32 v6, v86, v6
	v_add_f32_e32 v7, v87, v7
	ds_read_b32 v15, v31 offset:128
	ds_read_b32 v16, v31 offset:108
	ds_read_b32 v17, v31 offset:104
	ds_read_b32 v18, v31 offset:100
	ds_read_b32 v19, v31 offset:96
	ds_read_b32 v20, v31 offset:76
	ds_read_b32 v21, v31 offset:72
	ds_read_b32 v22, v31 offset:68
	v_exp_f32_e32 v0, v0
	v_exp_f32_e32 v1, v1
	v_exp_f32_e32 v2, v2
	v_exp_f32_e32 v3, v3
	v_exp_f32_e32 v4, v4
	v_exp_f32_e32 v5, v5
	v_exp_f32_e32 v6, v6
	v_exp_f32_e32 v7, v7
	s_waitcnt lgkmcnt(8)
	v_add_f32_e32 v8, v88, v8
	v_add_f32_e32 v9, v89, v9
	v_add_f32_e32 v10, v90, v10
	v_add_f32_e32 v11, v91, v11
	v_add_f32_e32 v12, v92, v12
	v_add_f32_e32 v13, v93, v13
	v_add_f32_e32 v14, v94, v14
	ds_read_b32 v23, v31 offset:64
	ds_read_b32 v24, v31 offset:44
	ds_read_b32 v25, v31 offset:40
	ds_read_b32 v26, v31 offset:36
	ds_read_b32 v27, v31 offset:32
	ds_read_b32 v28, v31 offset:12
	ds_read_b32 v29, v31 offset:8
	v_exp_f32_e32 v8, v8
	v_add_f32_e32 v156, v153, v0
	v_exp_f32_e32 v9, v9
	v_add_f32_e32 v156, v156, v1
	v_exp_f32_e32 v10, v10
	v_add_f32_e32 v156, v156, v2
	v_exp_f32_e32 v11, v11
	v_add_f32_e32 v156, v156, v3
	v_exp_f32_e32 v12, v12
	v_add_f32_e32 v156, v156, v4
	v_exp_f32_e32 v13, v13
	v_add_f32_e32 v156, v156, v5
	v_exp_f32_e32 v14, v14
	v_add_f32_e32 v156, v156, v6
	v_add_f32_e32 v156, v156, v7
	s_waitcnt lgkmcnt(7)
	v_add_f32_e32 v15, v95, v15
	v_add_f32_e32 v16, v64, v16
	v_add_f32_e32 v17, v65, v17
	v_add_f32_e32 v18, v66, v18
	v_add_f32_e32 v19, v67, v19
	v_add_f32_e32 v20, v68, v20
	v_add_f32_e32 v21, v69, v21
	v_add_f32_e32 v22, v70, v22
	ds_read_b32 v30, v31 offset:4
	ds_read_b32 v31, v31 offset:0
	v_exp_f32_e32 v15, v15
	v_add_f32_e32 v156, v156, v8
	v_exp_f32_e32 v16, v16
	v_add_f32_e32 v156, v156, v9
	v_exp_f32_e32 v17, v17
	v_add_f32_e32 v156, v156, v10
	v_exp_f32_e32 v18, v18
	v_add_f32_e32 v156, v156, v11
	v_exp_f32_e32 v19, v19
	v_add_f32_e32 v156, v156, v12
	v_exp_f32_e32 v20, v20
	v_add_f32_e32 v156, v156, v13
	v_exp_f32_e32 v21, v21
	v_add_f32_e32 v156, v156, v14
	v_exp_f32_e32 v22, v22
	s_waitcnt lgkmcnt(2)
	v_add_f32_e32 v23, v71, v23
	v_add_f32_e32 v24, v72, v24
	v_add_f32_e32 v25, v73, v25
	v_add_f32_e32 v26, v74, v26
	v_add_f32_e32 v27, v75, v27
	v_add_f32_e32 v28, v76, v28
	v_add_f32_e32 v29, v77, v29
	v_exp_f32_e32 v23, v23
	v_add_f32_e32 v156, v156, v15
	v_exp_f32_e32 v24, v24
	v_add_f32_e32 v156, v156, v16
	v_exp_f32_e32 v25, v25
	v_add_f32_e32 v156, v156, v17
	v_exp_f32_e32 v26, v26
	v_add_f32_e32 v156, v156, v18
	v_exp_f32_e32 v27, v27
	v_add_f32_e32 v156, v156, v19
	v_exp_f32_e32 v28, v28
	v_add_f32_e32 v156, v156, v20
	v_exp_f32_e32 v29, v29
	v_add_f32_e32 v156, v156, v21
	v_add_f32_e32 v156, v156, v22
	s_waitcnt lgkmcnt(0)
	v_add_f32_e32 v30, v78, v30
	v_add_f32_e32 v31, v79, v31
	v_exp_f32_e32 v30, v30
	v_add_f32_e32 v156, v156, v23
	v_exp_f32_e32 v31, v31
	v_add_f32_e32 v156, v156, v24
	v_add_f32_e32 v156, v156, v25
	v_add_f32_e32 v156, v156, v26
	v_add_f32_e32 v156, v156, v27
	v_add_f32_e32 v156, v156, v28
	v_add_f32_e32 v156, v156, v29
	v_add_f32_e32 v156, v156, v30
	v_add_f32_e32 v156, v156, v31
	s_mov_b64 s[2:3], 0

.LBB0_624:
	s_andn2_b64 vcc, exec, s[2:3]
	s_cbranch_vccnz .LBB0_693
	s_lshl_b32 s2, s7, 6
	v_subrev_u32_e32 v0, s2, v228
	v_add_u32_e32 v154, v0, v164
	s_andn2_b64 vcc, exec, s[0:1]
	s_mov_b64 s[0:1], -1
	s_cbranch_vccnz .LBB0_691
	s_lshl_b32 s0, s33, 1
	s_add_i32 s0, s0, 0xfffff114
	v_lshl_add_u32 v31, v154, 2, s0
	ds_read_b32 v0, v31 offset:236
	ds_read_b32 v1, v31 offset:232
	ds_read_b32 v2, v31 offset:228
	ds_read_b32 v3, v31 offset:224
	ds_read_b32 v4, v31 offset:204
	ds_read_b32 v5, v31 offset:200
	ds_read_b32 v6, v31 offset:196
	ds_read_b32 v7, v31 offset:192
	ds_read_b32 v8, v31 offset:172
	ds_read_b32 v9, v31 offset:168
	ds_read_b32 v10, v31 offset:164
	ds_read_b32 v11, v31 offset:160
	ds_read_b32 v12, v31 offset:140
	ds_read_b32 v13, v31 offset:136
	ds_read_b32 v14, v31 offset:132
	s_waitcnt lgkmcnt(7)
	v_add_f32_e32 v0, v80, v0
	v_add_f32_e32 v1, v81, v1
	v_add_f32_e32 v2, v82, v2
	v_add_f32_e32 v3, v83, v3
	v_add_f32_e32 v4, v84, v4
	v_add_f32_e32 v5, v85, v5
	v_add_f32_e32 v6, v86, v6
	v_add_f32_e32 v7, v87, v7
	ds_read_b32 v15, v31 offset:128
	ds_read_b32 v16, v31 offset:108
	ds_read_b32 v17, v31 offset:104
	ds_read_b32 v18, v31 offset:100
	ds_read_b32 v19, v31 offset:96
	ds_read_b32 v20, v31 offset:76
	ds_read_b32 v21, v31 offset:72
	ds_read_b32 v22, v31 offset:68
	v_exp_f32_e32 v0, v0
	v_exp_f32_e32 v1, v1
	v_exp_f32_e32 v2, v2
	v_exp_f32_e32 v3, v3
	v_exp_f32_e32 v4, v4
	v_exp_f32_e32 v5, v5
	v_exp_f32_e32 v6, v6
	v_exp_f32_e32 v7, v7
	s_waitcnt lgkmcnt(8)
	v_add_f32_e32 v8, v88, v8
	v_add_f32_e32 v9, v89, v9
	v_add_f32_e32 v10, v90, v10
	v_add_f32_e32 v11, v91, v11
	v_add_f32_e32 v12, v92, v12
	v_add_f32_e32 v13, v93, v13
	v_add_f32_e32 v14, v94, v14
	ds_read_b32 v23, v31 offset:64
	ds_read_b32 v24, v31 offset:44
	ds_read_b32 v25, v31 offset:40
	ds_read_b32 v26, v31 offset:36
	ds_read_b32 v27, v31 offset:32
	ds_read_b32 v28, v31 offset:12
	ds_read_b32 v29, v31 offset:8
	v_exp_f32_e32 v8, v8
	v_add_f32_e32 v155, v153, v0
	v_exp_f32_e32 v9, v9
	v_add_f32_e32 v155, v155, v1
	v_exp_f32_e32 v10, v10
	v_add_f32_e32 v155, v155, v2
	v_exp_f32_e32 v11, v11
	v_add_f32_e32 v155, v155, v3
	v_exp_f32_e32 v12, v12
	v_add_f32_e32 v155, v155, v4
	v_exp_f32_e32 v13, v13
	v_add_f32_e32 v155, v155, v5
	v_exp_f32_e32 v14, v14
	v_add_f32_e32 v155, v155, v6
	v_add_f32_e32 v155, v155, v7
	s_waitcnt lgkmcnt(7)
	v_add_f32_e32 v15, v95, v15
	v_add_f32_e32 v16, v64, v16
	v_add_f32_e32 v17, v65, v17
	v_add_f32_e32 v18, v66, v18
	v_add_f32_e32 v19, v67, v19
	v_add_f32_e32 v20, v68, v20
	v_add_f32_e32 v21, v69, v21
	v_add_f32_e32 v22, v70, v22
	ds_read_b32 v30, v31 offset:4
	ds_read_b32 v31, v31 offset:0
	v_exp_f32_e32 v15, v15
	v_add_f32_e32 v155, v155, v8
	v_exp_f32_e32 v16, v16
	v_add_f32_e32 v155, v155, v9
	v_exp_f32_e32 v17, v17
	v_add_f32_e32 v155, v155, v10
	v_exp_f32_e32 v18, v18
	v_add_f32_e32 v155, v155, v11
	v_exp_f32_e32 v19, v19
	v_add_f32_e32 v155, v155, v12
	v_exp_f32_e32 v20, v20
	v_add_f32_e32 v155, v155, v13
	v_exp_f32_e32 v21, v21
	v_add_f32_e32 v155, v155, v14
	v_exp_f32_e32 v22, v22
	s_waitcnt lgkmcnt(2)
	v_add_f32_e32 v23, v71, v23
	v_add_f32_e32 v24, v72, v24
	v_add_f32_e32 v25, v73, v25
	v_add_f32_e32 v26, v74, v26
	v_add_f32_e32 v27, v75, v27
	v_add_f32_e32 v28, v76, v28
	v_add_f32_e32 v29, v77, v29
	v_exp_f32_e32 v23, v23
	v_add_f32_e32 v155, v155, v15
	v_exp_f32_e32 v24, v24
	v_add_f32_e32 v155, v155, v16
	v_exp_f32_e32 v25, v25
	v_add_f32_e32 v155, v155, v17
	v_exp_f32_e32 v26, v26
	v_add_f32_e32 v155, v155, v18
	v_exp_f32_e32 v27, v27
	v_add_f32_e32 v155, v155, v19
	v_exp_f32_e32 v28, v28
	v_add_f32_e32 v155, v155, v20
	v_exp_f32_e32 v29, v29
	v_add_f32_e32 v155, v155, v21
	v_add_f32_e32 v155, v155, v22
	s_waitcnt lgkmcnt(0)
	v_add_f32_e32 v30, v78, v30
	v_add_f32_e32 v31, v79, v31
	v_exp_f32_e32 v30, v30
	v_add_f32_e32 v155, v155, v23
	v_exp_f32_e32 v31, v31
	v_add_f32_e32 v155, v155, v24
	v_add_f32_e32 v155, v155, v25
	v_add_f32_e32 v155, v155, v26
	v_add_f32_e32 v155, v155, v27
	v_add_f32_e32 v155, v155, v28
	v_add_f32_e32 v155, v155, v29
	v_add_f32_e32 v155, v155, v30
	v_add_f32_e32 v155, v155, v31
	s_mov_b64 s[0:1], 0

	.amdhsa_kernel _Z8yoco_fwd4Args
		.amdhsa_group_segment_fixed_size 0
		.amdhsa_private_segment_fixed_size 0
		.amdhsa_kernarg_size 568
		.amdhsa_user_sgpr_count 2
		.amdhsa_user_sgpr_dispatch_ptr 0
		.amdhsa_user_sgpr_queue_ptr 0
		.amdhsa_user_sgpr_kernarg_segment_ptr 1
		.amdhsa_user_sgpr_dispatch_id 0
		.amdhsa_user_sgpr_kernarg_preload_length 0
		.amdhsa_user_sgpr_kernarg_preload_offset 0
		.amdhsa_user_sgpr_private_segment_size 0
		.amdhsa_uses_dynamic_stack 0
		.amdhsa_enable_private_segment 0
		.amdhsa_system_sgpr_workgroup_id_x 1
		.amdhsa_system_sgpr_workgroup_id_y 0
		.amdhsa_system_sgpr_workgroup_id_z 0
		.amdhsa_system_sgpr_workgroup_info 0
		.amdhsa_system_vgpr_workitem_id 2
		.amdhsa_next_free_vgpr 256
		.amdhsa_next_free_sgpr 102
		.amdhsa_accum_offset 256
		.amdhsa_reserve_vcc 1
		.amdhsa_float_round_mode_32 0
		.amdhsa_float_round_mode_16_64 0
		.amdhsa_float_denorm_mode_32 3
		.amdhsa_float_denorm_mode_16_64 3
		.amdhsa_dx10_clamp 1
		.amdhsa_ieee_mode 1
		.amdhsa_fp16_overflow 0
		.amdhsa_tg_split 0
		.amdhsa_exception_fp_ieee_invalid_op 0
		.amdhsa_exception_fp_denorm_src 0
		.amdhsa_exception_fp_ieee_div_zero 0
		.amdhsa_exception_fp_ieee_overflow 0
		.amdhsa_exception_fp_ieee_underflow 0
		.amdhsa_exception_fp_ieee_inexact 0
		.amdhsa_exception_int_div_zero 0
	.end_amdhsa_kernel

amdhsa.kernels:
  - .agpr_count:     0
    .args:
      - .offset:         0
        .size:           312
        .value_kind:     by_value
      - .offset:         312
        .size:           4
        .value_kind:     hidden_block_count_x
      - .offset:         316
        .size:           4
        .value_kind:     hidden_block_count_y
      - .offset:         320
        .size:           4
        .value_kind:     hidden_block_count_z
      - .offset:         324
        .size:           2
        .value_kind:     hidden_group_size_x
      - .offset:         326
        .size:           2
        .value_kind:     hidden_group_size_y
      - .offset:         328
        .size:           2
        .value_kind:     hidden_group_size_z
      - .offset:         330
        .size:           2
        .value_kind:     hidden_remainder_x
      - .offset:         332
        .size:           2
        .value_kind:     hidden_remainder_y
      - .offset:         334
        .size:           2
        .value_kind:     hidden_remainder_z
      - .offset:         352
        .size:           8
        .value_kind:     hidden_global_offset_x
      - .offset:         360
        .size:           8
        .value_kind:     hidden_global_offset_y
      - .offset:         368
        .size:           8
        .value_kind:     hidden_global_offset_z
      - .offset:         376
        .size:           2
        .value_kind:     hidden_grid_dims
      - .offset:         400
        .size:           8
        .value_kind:     hidden_multigrid_sync_arg
      - .offset:         432
        .size:           4
        .value_kind:     hidden_dynamic_lds_size
    .group_segment_fixed_size: 0
    .kernarg_segment_align: 8
    .kernarg_segment_size: 568
    .language:       OpenCL C
    .language_version:
      - 2
      - 0
    .max_flat_workgroup_size: 512
    .name:           _Z8yoco_fwd4Args
    .private_segment_fixed_size: 0
    .sgpr_count:     108
    .sgpr_spill_count: 444
    .symbol:         _Z8yoco_fwd4Args.kd
    .uniform_work_group_size: 1
    .uses_dynamic_stack: false
    .vgpr_count:     256
    .vgpr_spill_count: 0
    .wavefront_size: 64
